# diff-attention S-waves: QK MFMAs issued as two 8-long accumulate chains (K fragments read row-block first), on top of GEMM MFMA chain ordering
# speedup vs baseline: 1.0029x; 1.0029x over previous
.LBB0_1360:
	s_nop 9
	v_max_f32_e32 v101, v5, v5
	v_max_f32_e32 v103, v4, v4
	v_max_f32_e32 v101, v103, v101
	v_max3_f32 v101, v101, v6, v7
	v_max3_f32 v101, v101, v8, v9
	v_max3_f32 v101, v101, v10, v11
	v_max3_f32 v101, v101, v12, v13
	v_max3_f32 v101, v101, v14, v15
	v_max3_f32 v101, v101, v16, v17
	v_max3_f32 v101, v101, v18, v19
	v_max3_f32 v101, v101, v20, v21
	v_max3_f32 v101, v101, v22, v23
	v_max3_f32 v101, v101, v24, v25
	v_max3_f32 v101, v101, v26, v27
	v_max3_f32 v101, v101, v28, v29
	v_max3_f32 v101, v101, v30, v31
	v_max3_f32 v101, v101, v32, v33
	v_max3_f32 v101, v101, v34, v35
	v_mov_b32_e32 v103, v101
	s_nop 1
	v_permlane32_swap_b32_e32 v101, v103
	v_max_f32_e32 v103, v103, v103
	v_max_f32_e32 v101, v101, v101
	v_max_f32_e32 v101, v101, v103
	v_sub_f32_e32 v103, v101, v102
	v_cmp_ge_f32_e32 vcc, s34, v103
	v_max_f32_e32 v103, v102, v102
	v_max_f32_e32 v103, v103, v101
	v_sub_f32_e32 v101, v102, v103
	v_mul_f32_e32 v101, 0x3fb8aa3b, v101
	v_exp_f32_e32 v101, v101
	s_cmp_eq_u64 vcc, exec
	s_cselect_b64 vcc, -1, 0
	v_cndmask_b32_e64 v101, v101, 1.0, vcc
	v_cmp_gt_f32_e64 s[0:1], 1.0, v101
	s_cmp_lg_u64 s[0:1], 0
	s_cselect_b64 s[0:1], -1, 0
	s_and_b64 s[78:79], s[0:1], s[2:3]
	s_and_saveexec_b64 s[20:21], s[78:79]
	ds_write_b32 v2, v101
	s_or_b64 exec, exec, s[20:21]
	s_and_saveexec_b64 s[20:21], s[4:5]
	v_cndmask_b32_e64 v104, 0, 1, s[0:1]
	s_add_i32 s0, s59, 0
	s_add_i32 s0, s0, 0x20000
	v_mov_b32_e32 v105, s0
	ds_write_b32 v105, v104
	s_or_b64 exec, exec, s[20:21]
	s_add_i32 s0, s70, -3
	s_cmp_ge_u32 s0, s36
	v_add_u32_e32 v104, s72, v184
	s_cbranch_scc1 .LBB0_1366
	s_mul_hi_u32 s0, s68, 0xaaaaaaab
	s_lshr_b32 s0, s0, 1
	s_mul_i32 s0, s0, 0xc000
	v_subrev_u32_e32 v36, s0, v190
	v_subrev_u32_e32 v40, s0, v192
	v_subrev_u32_e32 v41, s0, v194
	v_subrev_u32_e32 v42, s0, v196
	v_subrev_u32_e32 v43, s0, v198
	v_subrev_u32_e32 v44, s0, v200
	v_subrev_u32_e32 v45, s0, v202
	v_subrev_u32_e32 v46, s0, v203
	v_add_u32_e32 v47, v104, v36
	v_add_u32_e32 v40, v104, v40
	v_add_u32_e32 v41, v104, v41
	v_add_u32_e32 v42, v104, v42
	v_add_u32_e32 v43, v104, v43
	v_add_u32_e32 v44, v104, v44
	v_add_u32_e32 v45, v104, v45
	v_add_u32_e32 v46, v104, v46
	ds_read_b128 v[36:39], v47
	ds_read_b128 v[106:109], v40
	ds_read_b128 v[114:117], v41
	ds_read_b128 v[122:125], v42
	ds_read_b128 v[130:133], v43
	ds_read_b128 v[138:141], v44
	ds_read_b128 v[146:149], v45
	ds_read_b128 v[214:217], v46
	ds_read_b128 v[52:55], v47 offset:8192
	ds_read_b128 v[110:113], v40 offset:8192
	ds_read_b128 v[118:121], v41 offset:8192
	ds_read_b128 v[126:129], v42 offset:8192
	ds_read_b128 v[134:137], v43 offset:8192
	ds_read_b128 v[142:145], v44 offset:8192
	ds_read_b128 v[150:153], v45 offset:8192
	ds_read_b128 v[218:221], v46 offset:8192
	s_waitcnt lgkmcnt(14)
	v_mfma_f32_32x32x16_bf16 v[36:51], v[36:39], v[68:71], 0
	v_cndmask_b32_e32 v102, v103, v102, vcc
	v_mul_f32_e32 v103, 0xbfb8aa3b, v102
	v_fmamk_f32 v4, v4, 0x3fb8aa3b, v103
	v_fmamk_f32 v5, v5, 0x3fb8aa3b, v103
	v_exp_f32_e32 v4, v4
	v_fmamk_f32 v6, v6, 0x3fb8aa3b, v103
	v_exp_f32_e32 v5, v5
	v_mfma_f32_32x32x16_bf16 v[36:51], v[106:109], v[72:75], v[36:51]
	v_fmamk_f32 v7, v7, 0x3fb8aa3b, v103
	v_exp_f32_e32 v6, v6
	v_fmamk_f32 v8, v8, 0x3fb8aa3b, v103
	v_fmamk_f32 v9, v9, 0x3fb8aa3b, v103
	v_fmamk_f32 v10, v10, 0x3fb8aa3b, v103
	v_fmamk_f32 v11, v11, 0x3fb8aa3b, v103
	v_fmamk_f32 v12, v12, 0x3fb8aa3b, v103
	s_waitcnt lgkmcnt(13)
	v_mfma_f32_32x32x16_bf16 v[36:51], v[114:117], v[76:79], v[36:51]
	v_fmamk_f32 v13, v13, 0x3fb8aa3b, v103
	v_fmamk_f32 v14, v14, 0x3fb8aa3b, v103
	v_fmamk_f32 v15, v15, 0x3fb8aa3b, v103
	v_fmamk_f32 v16, v16, 0x3fb8aa3b, v103
	v_fmamk_f32 v17, v17, 0x3fb8aa3b, v103
	v_fmamk_f32 v18, v18, 0x3fb8aa3b, v103
	v_fmamk_f32 v19, v19, 0x3fb8aa3b, v103
	v_fmamk_f32 v20, v20, 0x3fb8aa3b, v103
	s_waitcnt lgkmcnt(12)
	v_mfma_f32_32x32x16_bf16 v[36:51], v[122:125], v[80:83], v[36:51]
	v_fmamk_f32 v21, v21, 0x3fb8aa3b, v103
	v_fmamk_f32 v22, v22, 0x3fb8aa3b, v103
	v_fmamk_f32 v23, v23, 0x3fb8aa3b, v103
	v_fmamk_f32 v24, v24, 0x3fb8aa3b, v103
	v_fmamk_f32 v25, v25, 0x3fb8aa3b, v103
	v_fmamk_f32 v26, v26, 0x3fb8aa3b, v103
	v_fmamk_f32 v27, v27, 0x3fb8aa3b, v103
	v_fmamk_f32 v28, v28, 0x3fb8aa3b, v103
	s_waitcnt lgkmcnt(11)
	v_mfma_f32_32x32x16_bf16 v[36:51], v[130:133], v[84:87], v[36:51]
	v_fmamk_f32 v29, v29, 0x3fb8aa3b, v103
	v_fmamk_f32 v30, v30, 0x3fb8aa3b, v103
	v_fmamk_f32 v31, v31, 0x3fb8aa3b, v103
	v_fmamk_f32 v32, v32, 0x3fb8aa3b, v103
	v_fmamk_f32 v33, v33, 0x3fb8aa3b, v103
	v_fmamk_f32 v34, v34, 0x3fb8aa3b, v103
	v_fmac_f32_e32 v103, 0x3fb8aa3b, v35
	v_exp_f32_e32 v7, v7
	s_waitcnt lgkmcnt(10)
	v_mfma_f32_32x32x16_bf16 v[36:51], v[138:141], v[88:91], v[36:51]
	v_exp_f32_e32 v8, v8
	v_exp_f32_e32 v35, v103
	v_add_f32_e32 v103, 0, v4
	v_exp_f32_e32 v9, v9
	s_waitcnt lgkmcnt(9)
	v_mfma_f32_32x32x16_bf16 v[36:51], v[146:149], v[92:95], v[36:51]
	v_add_f32_e32 v103, v5, v103
	v_exp_f32_e32 v10, v10
	v_add_f32_e32 v103, v6, v103
	v_exp_f32_e32 v11, v11
	v_add_f32_e32 v103, v7, v103
	v_exp_f32_e32 v12, v12
	s_waitcnt lgkmcnt(8)
	v_mfma_f32_32x32x16_bf16 v[36:51], v[214:217], v[96:99], v[36:51]
	v_add_f32_e32 v103, v8, v103
	v_exp_f32_e32 v13, v13
	v_add_f32_e32 v103, v9, v103
	v_exp_f32_e32 v14, v14
	v_add_f32_e32 v103, v10, v103
	s_waitcnt lgkmcnt(7)
	v_mfma_f32_32x32x16_bf16 v[52:67], v[52:55], v[68:71], 0
	v_exp_f32_e32 v15, v15
	v_add_f32_e32 v103, v11, v103
	v_exp_f32_e32 v16, v16
	v_add_f32_e32 v103, v12, v103
	v_exp_f32_e32 v17, v17
	s_waitcnt lgkmcnt(6)
	v_mfma_f32_32x32x16_bf16 v[52:67], v[110:113], v[72:75], v[52:67]
	v_add_f32_e32 v103, v13, v103
	v_exp_f32_e32 v18, v18
	v_add_f32_e32 v103, v14, v103
	v_exp_f32_e32 v19, v19
	v_add_f32_e32 v103, v15, v103
	v_exp_f32_e32 v20, v20
	s_waitcnt lgkmcnt(5)
	v_mfma_f32_32x32x16_bf16 v[52:67], v[118:121], v[76:79], v[52:67]
	v_add_f32_e32 v103, v16, v103
	v_exp_f32_e32 v21, v21
	v_add_f32_e32 v103, v17, v103
	v_exp_f32_e32 v22, v22
	v_add_f32_e32 v103, v18, v103
	s_waitcnt lgkmcnt(4)
	v_mfma_f32_32x32x16_bf16 v[52:67], v[126:129], v[80:83], v[52:67]
	v_exp_f32_e32 v23, v23
	v_add_f32_e32 v103, v19, v103
	v_exp_f32_e32 v24, v24
	v_add_f32_e32 v103, v20, v103
	v_exp_f32_e32 v25, v25
	s_waitcnt lgkmcnt(3)
	v_mfma_f32_32x32x16_bf16 v[52:67], v[134:137], v[84:87], v[52:67]
	v_add_f32_e32 v103, v21, v103
	v_exp_f32_e32 v26, v26
	v_add_f32_e32 v103, v22, v103
	v_exp_f32_e32 v27, v27
	v_add_f32_e32 v103, v23, v103
	v_exp_f32_e32 v28, v28
	s_waitcnt lgkmcnt(2)
	v_mfma_f32_32x32x16_bf16 v[52:67], v[142:145], v[88:91], v[52:67]
	v_add_f32_e32 v103, v24, v103
	v_exp_f32_e32 v29, v29
	v_add_f32_e32 v103, v25, v103
	v_exp_f32_e32 v30, v30
	v_add_f32_e32 v103, v26, v103
	s_waitcnt lgkmcnt(1)
	v_mfma_f32_32x32x16_bf16 v[52:67], v[150:153], v[92:95], v[52:67]
	v_exp_f32_e32 v31, v31
	v_add_f32_e32 v103, v27, v103
	v_exp_f32_e32 v32, v32
	v_add_f32_e32 v103, v28, v103
	v_exp_f32_e32 v33, v33
	s_waitcnt lgkmcnt(0)
	v_mfma_f32_32x32x16_bf16 v[52:67], v[218:221], v[96:99], v[52:67]
	v_add_f32_e32 v103, v29, v103
	v_exp_f32_e32 v34, v34
	v_add_f32_e32 v103, v30, v103
	v_add_f32_e32 v103, v31, v103
	v_add_f32_e32 v103, v32, v103
	v_add_f32_e32 v103, v33, v103
	v_add_f32_e32 v103, v34, v103
	s_branch .Lds_join_s0

.LBB0_1373:
	s_mul_hi_u32 s0, s69, 0xaaaaaaab
	s_lshr_b32 s0, s0, 1
	s_mul_i32 s0, s0, 0xc000
	v_subrev_u32_e32 v8, s0, v186
	v_subrev_u32_e32 v9, s0, v189
	v_subrev_u32_e32 v10, s0, v191
	v_subrev_u32_e32 v11, s0, v193
	v_subrev_u32_e32 v12, s0, v195
	v_subrev_u32_e32 v13, s0, v197
	v_subrev_u32_e32 v14, s0, v199
	v_subrev_u32_e32 v4, s0, v201
	v_add_u32_e32 v15, v104, v4
	v_add_u32_e32 v14, v104, v14
	v_add_u32_e32 v13, v104, v13
	v_add_u32_e32 v12, v104, v12
	v_add_u32_e32 v11, v104, v11
	v_add_u32_e32 v10, v104, v10
	v_add_u32_e32 v9, v104, v9
	v_add_u32_e32 v8, v104, v8
	ds_read_b128 v[4:7], v15
	ds_read_b128 v[110:113], v14
	ds_read_b128 v[118:121], v13
	ds_read_b128 v[126:129], v12
	ds_read_b128 v[134:137], v11
	ds_read_b128 v[142:145], v10
	ds_read_b128 v[150:153], v9
	ds_read_b128 v[218:221], v8
	ds_read_b128 v[20:23], v15 offset:8192
	ds_read_b128 v[114:117], v14 offset:8192
	ds_read_b128 v[122:125], v13 offset:8192
	ds_read_b128 v[130:133], v12 offset:8192
	ds_read_b128 v[138:141], v11 offset:8192
	ds_read_b128 v[146:149], v10 offset:8192
	ds_read_b128 v[214:217], v9 offset:8192
	ds_read_b128 v[222:225], v8 offset:8192
	s_waitcnt lgkmcnt(14)
	v_mfma_f32_32x32x16_bf16 v[4:19], v[4:7], v[68:71], 0
	v_cndmask_b32_e32 v102, v108, v102, vcc
	v_mul_f32_e32 v104, 0xbfb8aa3b, v102
	v_fmamk_f32 v36, v36, 0x3fb8aa3b, v104
	v_fmamk_f32 v37, v37, 0x3fb8aa3b, v104
	v_exp_f32_e32 v36, v36
	v_fmamk_f32 v38, v38, 0x3fb8aa3b, v104
	v_exp_f32_e32 v37, v37
	v_mfma_f32_32x32x16_bf16 v[4:19], v[110:113], v[72:75], v[4:19]
	v_fmamk_f32 v39, v39, 0x3fb8aa3b, v104
	v_exp_f32_e32 v38, v38
	v_fmamk_f32 v40, v40, 0x3fb8aa3b, v104
	v_exp_f32_e32 v39, v39
	v_add_f32_e32 v105, v105, v106
	v_fmamk_f32 v41, v41, 0x3fb8aa3b, v104
	s_waitcnt lgkmcnt(13)
	v_mfma_f32_32x32x16_bf16 v[4:19], v[118:121], v[76:79], v[4:19]
	v_exp_f32_e32 v40, v40
	v_fmac_f32_e32 v105, v100, v101
	v_add_f32_e32 v100, 0, v36
	v_fmamk_f32 v42, v42, 0x3fb8aa3b, v104
	v_exp_f32_e32 v41, v41
	v_add_f32_e32 v100, v37, v100
	v_fmamk_f32 v43, v43, 0x3fb8aa3b, v104
	s_waitcnt lgkmcnt(12)
	v_mfma_f32_32x32x16_bf16 v[4:19], v[126:129], v[80:83], v[4:19]
	v_exp_f32_e32 v42, v42
	v_add_f32_e32 v100, v38, v100
	v_fmamk_f32 v44, v44, 0x3fb8aa3b, v104
	v_exp_f32_e32 v43, v43
	v_add_f32_e32 v100, v39, v100
	v_fmamk_f32 v45, v45, 0x3fb8aa3b, v104
	s_waitcnt lgkmcnt(11)
	v_mfma_f32_32x32x16_bf16 v[4:19], v[134:137], v[84:87], v[4:19]
	v_exp_f32_e32 v44, v44
	v_add_f32_e32 v100, v40, v100
	v_fmamk_f32 v46, v46, 0x3fb8aa3b, v104
	v_exp_f32_e32 v45, v45
	v_add_f32_e32 v100, v41, v100
	v_fmamk_f32 v47, v47, 0x3fb8aa3b, v104
	v_exp_f32_e32 v46, v46
	s_waitcnt lgkmcnt(10)
	v_mfma_f32_32x32x16_bf16 v[4:19], v[142:145], v[88:91], v[4:19]
	v_add_f32_e32 v100, v42, v100
	v_fmamk_f32 v48, v48, 0x3fb8aa3b, v104
	v_exp_f32_e32 v47, v47
	v_add_f32_e32 v100, v43, v100
	v_fmamk_f32 v49, v49, 0x3fb8aa3b, v104
	v_exp_f32_e32 v48, v48
	s_waitcnt lgkmcnt(9)
	v_mfma_f32_32x32x16_bf16 v[4:19], v[150:153], v[92:95], v[4:19]
	v_add_f32_e32 v100, v44, v100
	v_fmamk_f32 v50, v50, 0x3fb8aa3b, v104
	v_exp_f32_e32 v49, v49
	v_add_f32_e32 v100, v45, v100
	v_fmamk_f32 v51, v51, 0x3fb8aa3b, v104
	v_exp_f32_e32 v50, v50
	s_waitcnt lgkmcnt(8)
	v_mfma_f32_32x32x16_bf16 v[4:19], v[218:221], v[96:99], v[4:19]
	v_add_f32_e32 v100, v46, v100
	v_fmamk_f32 v52, v52, 0x3fb8aa3b, v104
	v_exp_f32_e32 v51, v51
	v_add_f32_e32 v100, v47, v100
	v_fmamk_f32 v53, v53, 0x3fb8aa3b, v104
	v_exp_f32_e32 v52, v52
	s_waitcnt lgkmcnt(7)
	v_mfma_f32_32x32x16_bf16 v[20:35], v[20:23], v[68:71], 0
	v_add_f32_e32 v100, v48, v100
	v_fmamk_f32 v54, v54, 0x3fb8aa3b, v104
	v_exp_f32_e32 v53, v53
	v_add_f32_e32 v100, v49, v100
	v_fmamk_f32 v55, v55, 0x3fb8aa3b, v104
	v_exp_f32_e32 v54, v54
	s_waitcnt lgkmcnt(6)
	v_mfma_f32_32x32x16_bf16 v[20:35], v[114:117], v[72:75], v[20:35]
	v_add_f32_e32 v100, v50, v100
	v_fmamk_f32 v56, v56, 0x3fb8aa3b, v104
	v_exp_f32_e32 v55, v55
	v_add_f32_e32 v100, v51, v100
	v_fmamk_f32 v57, v57, 0x3fb8aa3b, v104
	v_exp_f32_e32 v56, v56
	v_add_f32_e32 v100, v52, v100
	s_waitcnt lgkmcnt(5)
	v_mfma_f32_32x32x16_bf16 v[20:35], v[122:125], v[76:79], v[20:35]
	v_fmamk_f32 v58, v58, 0x3fb8aa3b, v104
	v_exp_f32_e32 v57, v57
	v_add_f32_e32 v100, v53, v100
	v_fmamk_f32 v59, v59, 0x3fb8aa3b, v104
	v_exp_f32_e32 v58, v58
	v_add_f32_e32 v100, v54, v100
	s_waitcnt lgkmcnt(4)
	v_mfma_f32_32x32x16_bf16 v[20:35], v[130:133], v[80:83], v[20:35]
	v_fmamk_f32 v60, v60, 0x3fb8aa3b, v104
	v_exp_f32_e32 v59, v59
	v_add_f32_e32 v100, v55, v100
	v_fmamk_f32 v61, v61, 0x3fb8aa3b, v104
	v_exp_f32_e32 v60, v60
	v_add_f32_e32 v100, v56, v100
	v_fmamk_f32 v62, v62, 0x3fb8aa3b, v104
	s_waitcnt lgkmcnt(3)
	v_mfma_f32_32x32x16_bf16 v[20:35], v[138:141], v[84:87], v[20:35]
	v_exp_f32_e32 v61, v61
	v_add_f32_e32 v100, v57, v100
	v_fmamk_f32 v63, v63, 0x3fb8aa3b, v104
	v_exp_f32_e32 v62, v62
	v_add_f32_e32 v100, v58, v100
	v_fmamk_f32 v64, v64, 0x3fb8aa3b, v104
	s_waitcnt lgkmcnt(2)
	v_mfma_f32_32x32x16_bf16 v[20:35], v[146:149], v[88:91], v[20:35]
	v_exp_f32_e32 v63, v63
	v_add_f32_e32 v100, v59, v100
	v_fmamk_f32 v65, v65, 0x3fb8aa3b, v104
	v_exp_f32_e32 v64, v64
	v_add_f32_e32 v100, v60, v100
	v_fmamk_f32 v66, v66, 0x3fb8aa3b, v104
	v_exp_f32_e32 v65, v65
	s_waitcnt lgkmcnt(1)
	v_mfma_f32_32x32x16_bf16 v[20:35], v[214:217], v[92:95], v[20:35]
	v_add_f32_e32 v100, v61, v100
	v_fmac_f32_e32 v104, 0x3fb8aa3b, v67
	v_exp_f32_e32 v66, v66
	v_add_f32_e32 v100, v62, v100
	v_exp_f32_e32 v67, v104
	s_waitcnt lgkmcnt(0)
	v_mfma_f32_32x32x16_bf16 v[20:35], v[222:225], v[96:99], v[20:35]
	v_add_f32_e32 v100, v63, v100
	v_add_f32_e32 v100, v64, v100
	v_add_f32_e32 v100, v65, v100
	v_add_f32_e32 v100, v66, v100
	v_add_f32_e32 v100, v67, v100
	v_mov_b32_e32 v101, v100
	s_nop 1
	v_permlane32_swap_b32_e32 v100, v101
	s_branch .Lds_join_s1

.LBB0_1392:
	s_nop 9
	v_max_f32_e32 v101, v5, v5
	v_max_f32_e32 v103, v4, v4
	v_max_f32_e32 v101, v103, v101
	v_max3_f32 v101, v101, v6, v7
	v_max3_f32 v101, v101, v8, v9
	v_max3_f32 v101, v101, v10, v11
	v_max3_f32 v101, v101, v12, v13
	v_max3_f32 v101, v101, v14, v15
	v_max3_f32 v101, v101, v16, v17
	v_max3_f32 v101, v101, v18, v19
	v_max3_f32 v101, v101, v20, v21
	v_max3_f32 v101, v101, v22, v23
	v_max3_f32 v101, v101, v24, v25
	v_max3_f32 v101, v101, v26, v27
	v_max3_f32 v101, v101, v28, v29
	v_max3_f32 v101, v101, v30, v31
	v_max3_f32 v101, v101, v32, v33
	v_max3_f32 v101, v101, v34, v35
	v_mov_b32_e32 v103, v101
	s_nop 1
	v_permlane32_swap_b32_e32 v101, v103
	v_max_f32_e32 v103, v103, v103
	v_max_f32_e32 v101, v101, v101
	v_max_f32_e32 v101, v101, v103
	v_sub_f32_e32 v103, v101, v102
	v_cmp_ge_f32_e32 vcc, s34, v103
	v_max_f32_e32 v103, v102, v102
	v_max_f32_e32 v103, v103, v101
	v_sub_f32_e32 v101, v102, v103
	v_mul_f32_e32 v101, 0x3fb8aa3b, v101
	v_exp_f32_e32 v101, v101
	s_cmp_eq_u64 vcc, exec
	s_cselect_b64 vcc, -1, 0
	v_cndmask_b32_e64 v101, v101, 1.0, vcc
	v_cmp_gt_f32_e64 s[0:1], 1.0, v101
	s_cmp_lg_u64 s[0:1], 0
	s_cselect_b64 s[0:1], -1, 0
	s_and_b64 s[66:67], s[0:1], s[2:3]
	s_and_saveexec_b64 s[14:15], s[66:67]
	ds_write_b32 v2, v101
	s_or_b64 exec, exec, s[14:15]
	s_and_saveexec_b64 s[14:15], s[4:5]
	v_cndmask_b32_e64 v104, 0, 1, s[0:1]
	s_add_i32 s0, s19, 0
	s_add_i32 s0, s0, 0x20000
	v_mov_b32_e32 v105, s0
	ds_write_b32 v105, v104
	s_or_b64 exec, exec, s[14:15]
	s_add_i32 s0, s58, -3
	s_cmp_ge_u32 s0, s36
	v_add_u32_e32 v104, s60, v184
	s_cbranch_scc1 .LBB0_1398
	s_mul_hi_u32 s0, s56, 0xaaaaaaab
	s_lshr_b32 s0, s0, 1
	s_mul_i32 s0, s0, 0xc000
	v_subrev_u32_e32 v36, s0, v190
	v_subrev_u32_e32 v40, s0, v192
	v_subrev_u32_e32 v41, s0, v194
	v_subrev_u32_e32 v42, s0, v196
	v_subrev_u32_e32 v43, s0, v198
	v_subrev_u32_e32 v44, s0, v200
	v_subrev_u32_e32 v45, s0, v202
	v_subrev_u32_e32 v46, s0, v203
	v_add_u32_e32 v47, v104, v36
	v_add_u32_e32 v40, v104, v40
	v_add_u32_e32 v41, v104, v41
	v_add_u32_e32 v42, v104, v42
	v_add_u32_e32 v43, v104, v43
	v_add_u32_e32 v44, v104, v44
	v_add_u32_e32 v45, v104, v45
	v_add_u32_e32 v46, v104, v46
	ds_read_b128 v[36:39], v47
	ds_read_b128 v[106:109], v40
	ds_read_b128 v[114:117], v41
	ds_read_b128 v[122:125], v42
	ds_read_b128 v[130:133], v43
	ds_read_b128 v[138:141], v44
	ds_read_b128 v[146:149], v45
	ds_read_b128 v[154:157], v46
	ds_read_b128 v[52:55], v47 offset:8192
	ds_read_b128 v[110:113], v40 offset:8192
	ds_read_b128 v[118:121], v41 offset:8192
	ds_read_b128 v[126:129], v42 offset:8192
	ds_read_b128 v[134:137], v43 offset:8192
	ds_read_b128 v[142:145], v44 offset:8192
	ds_read_b128 v[150:153], v45 offset:8192
	ds_read_b128 v[214:217], v46 offset:8192
	s_waitcnt lgkmcnt(14)
	v_mfma_f32_32x32x16_bf16 v[36:51], v[36:39], v[68:71], 0
	v_cndmask_b32_e32 v102, v103, v102, vcc
	v_mul_f32_e32 v103, 0xbfb8aa3b, v102
	v_fmamk_f32 v4, v4, 0x3fb8aa3b, v103
	v_fmamk_f32 v5, v5, 0x3fb8aa3b, v103
	v_exp_f32_e32 v4, v4
	v_fmamk_f32 v6, v6, 0x3fb8aa3b, v103
	v_exp_f32_e32 v5, v5
	v_mfma_f32_32x32x16_bf16 v[36:51], v[106:109], v[72:75], v[36:51]
	v_fmamk_f32 v7, v7, 0x3fb8aa3b, v103
	v_exp_f32_e32 v6, v6
	v_fmamk_f32 v8, v8, 0x3fb8aa3b, v103
	v_fmamk_f32 v9, v9, 0x3fb8aa3b, v103
	v_fmamk_f32 v10, v10, 0x3fb8aa3b, v103
	v_fmamk_f32 v11, v11, 0x3fb8aa3b, v103
	v_fmamk_f32 v12, v12, 0x3fb8aa3b, v103
	s_waitcnt lgkmcnt(13)
	v_mfma_f32_32x32x16_bf16 v[36:51], v[114:117], v[76:79], v[36:51]
	v_fmamk_f32 v13, v13, 0x3fb8aa3b, v103
	v_fmamk_f32 v14, v14, 0x3fb8aa3b, v103
	v_fmamk_f32 v15, v15, 0x3fb8aa3b, v103
	v_fmamk_f32 v16, v16, 0x3fb8aa3b, v103
	v_fmamk_f32 v17, v17, 0x3fb8aa3b, v103
	v_fmamk_f32 v18, v18, 0x3fb8aa3b, v103
	v_fmamk_f32 v19, v19, 0x3fb8aa3b, v103
	v_fmamk_f32 v20, v20, 0x3fb8aa3b, v103
	s_waitcnt lgkmcnt(12)
	v_mfma_f32_32x32x16_bf16 v[36:51], v[122:125], v[80:83], v[36:51]
	v_fmamk_f32 v21, v21, 0x3fb8aa3b, v103
	v_fmamk_f32 v22, v22, 0x3fb8aa3b, v103
	v_fmamk_f32 v23, v23, 0x3fb8aa3b, v103
	v_fmamk_f32 v24, v24, 0x3fb8aa3b, v103
	v_fmamk_f32 v25, v25, 0x3fb8aa3b, v103
	v_fmamk_f32 v26, v26, 0x3fb8aa3b, v103
	v_fmamk_f32 v27, v27, 0x3fb8aa3b, v103
	v_fmamk_f32 v28, v28, 0x3fb8aa3b, v103
	s_waitcnt lgkmcnt(11)
	v_mfma_f32_32x32x16_bf16 v[36:51], v[130:133], v[84:87], v[36:51]
	v_fmamk_f32 v29, v29, 0x3fb8aa3b, v103
	v_fmamk_f32 v30, v30, 0x3fb8aa3b, v103
	v_fmamk_f32 v31, v31, 0x3fb8aa3b, v103
	v_fmamk_f32 v32, v32, 0x3fb8aa3b, v103
	v_fmamk_f32 v33, v33, 0x3fb8aa3b, v103
	v_fmamk_f32 v34, v34, 0x3fb8aa3b, v103
	v_fmac_f32_e32 v103, 0x3fb8aa3b, v35
	v_exp_f32_e32 v7, v7
	s_waitcnt lgkmcnt(10)
	v_mfma_f32_32x32x16_bf16 v[36:51], v[138:141], v[88:91], v[36:51]
	v_exp_f32_e32 v8, v8
	v_exp_f32_e32 v35, v103
	v_add_f32_e32 v103, 0, v4
	v_exp_f32_e32 v9, v9
	s_waitcnt lgkmcnt(9)
	v_mfma_f32_32x32x16_bf16 v[36:51], v[146:149], v[92:95], v[36:51]
	v_add_f32_e32 v103, v5, v103
	v_exp_f32_e32 v10, v10
	v_add_f32_e32 v103, v6, v103
	v_exp_f32_e32 v11, v11
	v_add_f32_e32 v103, v7, v103
	v_exp_f32_e32 v12, v12
	s_waitcnt lgkmcnt(8)
	v_mfma_f32_32x32x16_bf16 v[36:51], v[154:157], v[96:99], v[36:51]
	v_add_f32_e32 v103, v8, v103
	v_exp_f32_e32 v13, v13
	v_add_f32_e32 v103, v9, v103
	v_exp_f32_e32 v14, v14
	v_add_f32_e32 v103, v10, v103
	s_waitcnt lgkmcnt(7)
	v_mfma_f32_32x32x16_bf16 v[52:67], v[52:55], v[68:71], 0
	v_exp_f32_e32 v15, v15
	v_add_f32_e32 v103, v11, v103
	v_exp_f32_e32 v16, v16
	v_add_f32_e32 v103, v12, v103
	v_exp_f32_e32 v17, v17
	s_waitcnt lgkmcnt(6)
	v_mfma_f32_32x32x16_bf16 v[52:67], v[110:113], v[72:75], v[52:67]
	v_add_f32_e32 v103, v13, v103
	v_exp_f32_e32 v18, v18
	v_add_f32_e32 v103, v14, v103
	v_exp_f32_e32 v19, v19
	v_add_f32_e32 v103, v15, v103
	v_exp_f32_e32 v20, v20
	s_waitcnt lgkmcnt(5)
	v_mfma_f32_32x32x16_bf16 v[52:67], v[118:121], v[76:79], v[52:67]
	v_add_f32_e32 v103, v16, v103
	v_exp_f32_e32 v21, v21
	v_add_f32_e32 v103, v17, v103
	v_exp_f32_e32 v22, v22
	v_add_f32_e32 v103, v18, v103
	s_waitcnt lgkmcnt(4)
	v_mfma_f32_32x32x16_bf16 v[52:67], v[126:129], v[80:83], v[52:67]
	v_exp_f32_e32 v23, v23
	v_add_f32_e32 v103, v19, v103
	v_exp_f32_e32 v24, v24
	v_add_f32_e32 v103, v20, v103
	v_exp_f32_e32 v25, v25
	s_waitcnt lgkmcnt(3)
	v_mfma_f32_32x32x16_bf16 v[52:67], v[134:137], v[84:87], v[52:67]
	v_add_f32_e32 v103, v21, v103
	v_exp_f32_e32 v26, v26
	v_add_f32_e32 v103, v22, v103
	v_exp_f32_e32 v27, v27
	v_add_f32_e32 v103, v23, v103
	v_exp_f32_e32 v28, v28
	s_waitcnt lgkmcnt(2)
	v_mfma_f32_32x32x16_bf16 v[52:67], v[142:145], v[88:91], v[52:67]
	v_add_f32_e32 v103, v24, v103
	v_exp_f32_e32 v29, v29
	v_add_f32_e32 v103, v25, v103
	v_exp_f32_e32 v30, v30
	v_add_f32_e32 v103, v26, v103
	s_waitcnt lgkmcnt(1)
	v_mfma_f32_32x32x16_bf16 v[52:67], v[150:153], v[92:95], v[52:67]
	v_exp_f32_e32 v31, v31
	v_add_f32_e32 v103, v27, v103
	v_exp_f32_e32 v32, v32
	v_add_f32_e32 v103, v28, v103
	v_exp_f32_e32 v33, v33
	s_waitcnt lgkmcnt(0)
	v_mfma_f32_32x32x16_bf16 v[52:67], v[214:217], v[96:99], v[52:67]
	v_add_f32_e32 v103, v29, v103
	v_exp_f32_e32 v34, v34
	v_add_f32_e32 v103, v30, v103
	v_add_f32_e32 v103, v31, v103
	v_add_f32_e32 v103, v32, v103
	v_add_f32_e32 v103, v33, v103
	v_add_f32_e32 v103, v34, v103
	s_branch .Lds_join_s2

.LBB0_1405:
	s_mul_hi_u32 s0, s57, 0xaaaaaaab
	s_lshr_b32 s0, s0, 1
	s_mul_i32 s0, s0, 0xc000
	v_subrev_u32_e32 v8, s0, v186
	v_subrev_u32_e32 v9, s0, v189
	v_subrev_u32_e32 v10, s0, v191
	v_subrev_u32_e32 v11, s0, v193
	v_subrev_u32_e32 v12, s0, v195
	v_subrev_u32_e32 v13, s0, v197
	v_subrev_u32_e32 v14, s0, v199
	v_subrev_u32_e32 v4, s0, v201
	v_add_u32_e32 v15, v104, v4
	v_add_u32_e32 v14, v104, v14
	v_add_u32_e32 v13, v104, v13
	v_add_u32_e32 v12, v104, v12
	v_add_u32_e32 v11, v104, v11
	v_add_u32_e32 v10, v104, v10
	v_add_u32_e32 v9, v104, v9
	v_add_u32_e32 v8, v104, v8
	ds_read_b128 v[4:7], v15
	ds_read_b128 v[110:113], v14
	ds_read_b128 v[118:121], v13
	ds_read_b128 v[126:129], v12
	ds_read_b128 v[134:137], v11
	ds_read_b128 v[142:145], v10
	ds_read_b128 v[150:153], v9
	ds_read_b128 v[214:217], v8
	ds_read_b128 v[20:23], v15 offset:8192
	ds_read_b128 v[114:117], v14 offset:8192
	ds_read_b128 v[122:125], v13 offset:8192
	ds_read_b128 v[130:133], v12 offset:8192
	ds_read_b128 v[138:141], v11 offset:8192
	ds_read_b128 v[146:149], v10 offset:8192
	ds_read_b128 v[154:157], v9 offset:8192
	ds_read_b128 v[218:221], v8 offset:8192
	s_waitcnt lgkmcnt(14)
	v_mfma_f32_32x32x16_bf16 v[4:19], v[4:7], v[68:71], 0
	v_cndmask_b32_e32 v102, v108, v102, vcc
	v_mul_f32_e32 v104, 0xbfb8aa3b, v102
	v_fmamk_f32 v36, v36, 0x3fb8aa3b, v104
	v_fmamk_f32 v37, v37, 0x3fb8aa3b, v104
	v_exp_f32_e32 v36, v36
	v_fmamk_f32 v38, v38, 0x3fb8aa3b, v104
	v_exp_f32_e32 v37, v37
	v_mfma_f32_32x32x16_bf16 v[4:19], v[110:113], v[72:75], v[4:19]
	v_fmamk_f32 v39, v39, 0x3fb8aa3b, v104
	v_exp_f32_e32 v38, v38
	v_fmamk_f32 v40, v40, 0x3fb8aa3b, v104
	v_exp_f32_e32 v39, v39
	v_add_f32_e32 v105, v105, v106
	v_fmamk_f32 v41, v41, 0x3fb8aa3b, v104
	s_waitcnt lgkmcnt(13)
	v_mfma_f32_32x32x16_bf16 v[4:19], v[118:121], v[76:79], v[4:19]
	v_exp_f32_e32 v40, v40
	v_fmac_f32_e32 v105, v100, v101
	v_add_f32_e32 v100, 0, v36
	v_fmamk_f32 v42, v42, 0x3fb8aa3b, v104
	v_exp_f32_e32 v41, v41
	v_add_f32_e32 v100, v37, v100
	v_fmamk_f32 v43, v43, 0x3fb8aa3b, v104
	s_waitcnt lgkmcnt(12)
	v_mfma_f32_32x32x16_bf16 v[4:19], v[126:129], v[80:83], v[4:19]
	v_exp_f32_e32 v42, v42
	v_add_f32_e32 v100, v38, v100
	v_fmamk_f32 v44, v44, 0x3fb8aa3b, v104
	v_exp_f32_e32 v43, v43
	v_add_f32_e32 v100, v39, v100
	v_fmamk_f32 v45, v45, 0x3fb8aa3b, v104
	s_waitcnt lgkmcnt(11)
	v_mfma_f32_32x32x16_bf16 v[4:19], v[134:137], v[84:87], v[4:19]
	v_exp_f32_e32 v44, v44
	v_add_f32_e32 v100, v40, v100
	v_fmamk_f32 v46, v46, 0x3fb8aa3b, v104
	v_exp_f32_e32 v45, v45
	v_add_f32_e32 v100, v41, v100
	v_fmamk_f32 v47, v47, 0x3fb8aa3b, v104
	v_exp_f32_e32 v46, v46
	s_waitcnt lgkmcnt(10)
	v_mfma_f32_32x32x16_bf16 v[4:19], v[142:145], v[88:91], v[4:19]
	v_add_f32_e32 v100, v42, v100
	v_fmamk_f32 v48, v48, 0x3fb8aa3b, v104
	v_exp_f32_e32 v47, v47
	v_add_f32_e32 v100, v43, v100
	v_fmamk_f32 v49, v49, 0x3fb8aa3b, v104
	v_exp_f32_e32 v48, v48
	s_waitcnt lgkmcnt(9)
	v_mfma_f32_32x32x16_bf16 v[4:19], v[150:153], v[92:95], v[4:19]
	v_add_f32_e32 v100, v44, v100
	v_fmamk_f32 v50, v50, 0x3fb8aa3b, v104
	v_exp_f32_e32 v49, v49
	v_add_f32_e32 v100, v45, v100
	v_fmamk_f32 v51, v51, 0x3fb8aa3b, v104
	v_exp_f32_e32 v50, v50
	s_waitcnt lgkmcnt(8)
	v_mfma_f32_32x32x16_bf16 v[4:19], v[214:217], v[96:99], v[4:19]
	v_add_f32_e32 v100, v46, v100
	v_fmamk_f32 v52, v52, 0x3fb8aa3b, v104
	v_exp_f32_e32 v51, v51
	v_add_f32_e32 v100, v47, v100
	v_fmamk_f32 v53, v53, 0x3fb8aa3b, v104
	v_exp_f32_e32 v52, v52
	s_waitcnt lgkmcnt(7)
	v_mfma_f32_32x32x16_bf16 v[20:35], v[20:23], v[68:71], 0
	v_add_f32_e32 v100, v48, v100
	v_fmamk_f32 v54, v54, 0x3fb8aa3b, v104
	v_exp_f32_e32 v53, v53
	v_add_f32_e32 v100, v49, v100
	v_fmamk_f32 v55, v55, 0x3fb8aa3b, v104
	v_exp_f32_e32 v54, v54
	s_waitcnt lgkmcnt(6)
	v_mfma_f32_32x32x16_bf16 v[20:35], v[114:117], v[72:75], v[20:35]
	v_add_f32_e32 v100, v50, v100
	v_fmamk_f32 v56, v56, 0x3fb8aa3b, v104
	v_exp_f32_e32 v55, v55
	v_add_f32_e32 v100, v51, v100
	v_fmamk_f32 v57, v57, 0x3fb8aa3b, v104
	v_exp_f32_e32 v56, v56
	v_add_f32_e32 v100, v52, v100
	s_waitcnt lgkmcnt(5)
	v_mfma_f32_32x32x16_bf16 v[20:35], v[122:125], v[76:79], v[20:35]
	v_fmamk_f32 v58, v58, 0x3fb8aa3b, v104
	v_exp_f32_e32 v57, v57
	v_add_f32_e32 v100, v53, v100
	v_fmamk_f32 v59, v59, 0x3fb8aa3b, v104
	v_exp_f32_e32 v58, v58
	v_add_f32_e32 v100, v54, v100
	s_waitcnt lgkmcnt(4)
	v_mfma_f32_32x32x16_bf16 v[20:35], v[130:133], v[80:83], v[20:35]
	v_fmamk_f32 v60, v60, 0x3fb8aa3b, v104
	v_exp_f32_e32 v59, v59
	v_add_f32_e32 v100, v55, v100
	v_fmamk_f32 v61, v61, 0x3fb8aa3b, v104
	v_exp_f32_e32 v60, v60
	v_add_f32_e32 v100, v56, v100
	v_fmamk_f32 v62, v62, 0x3fb8aa3b, v104
	s_waitcnt lgkmcnt(3)
	v_mfma_f32_32x32x16_bf16 v[20:35], v[138:141], v[84:87], v[20:35]
	v_exp_f32_e32 v61, v61
	v_add_f32_e32 v100, v57, v100
	v_fmamk_f32 v63, v63, 0x3fb8aa3b, v104
	v_exp_f32_e32 v62, v62
	v_add_f32_e32 v100, v58, v100
	v_fmamk_f32 v64, v64, 0x3fb8aa3b, v104
	s_waitcnt lgkmcnt(2)
	v_mfma_f32_32x32x16_bf16 v[20:35], v[146:149], v[88:91], v[20:35]
	v_exp_f32_e32 v63, v63
	v_add_f32_e32 v100, v59, v100
	v_fmamk_f32 v65, v65, 0x3fb8aa3b, v104
	v_exp_f32_e32 v64, v64
	v_add_f32_e32 v100, v60, v100
	v_fmamk_f32 v66, v66, 0x3fb8aa3b, v104
	v_exp_f32_e32 v65, v65
	s_waitcnt lgkmcnt(1)
	v_mfma_f32_32x32x16_bf16 v[20:35], v[154:157], v[92:95], v[20:35]
	v_add_f32_e32 v100, v61, v100
	v_fmac_f32_e32 v104, 0x3fb8aa3b, v67
	v_exp_f32_e32 v66, v66
	v_add_f32_e32 v100, v62, v100
	v_exp_f32_e32 v67, v104
	s_waitcnt lgkmcnt(0)
	v_mfma_f32_32x32x16_bf16 v[20:35], v[218:221], v[96:99], v[20:35]
	v_add_f32_e32 v100, v63, v100
	v_add_f32_e32 v100, v64, v100
	v_add_f32_e32 v100, v65, v100
	v_add_f32_e32 v100, v66, v100
	v_add_f32_e32 v100, v67, v100
	v_mov_b32_e32 v101, v100
	s_nop 1
	v_permlane32_swap_b32_e32 v100, v101
	s_branch .Lds_join_s3
